# P5 resid epilogue: 32 serialized x loads hoisted into pipelined batches (on top of v16)
# speedup vs baseline: 1.0024x; 1.0024x over previous
; DI int get_tid(int wv) { int l; asm volatile("v_mbcnt_lo_u32_b32 %0, -1, 0\n\tv_mbcnt_hi_u32_b32 %0, -1, %0" : "=v"(l)); return wv * 64 + l; }
; DI int wave_of(int tid) { return __builtin_amdgcn_readfirstlane(tid >> 6); }
; DI void resid_norm_epi(WVP char* smem, AccT& acc, int bc0, const float* xin, float* xout, int n0, int pc, int pr, unsigned epoch,
;                        u64* slab, const float* g, u16* xn, int mode) {
;   const int t2 = get_tid(WV);
;   const int wid2 = wave_of(t2), lane2 = t2 & 63, wr2 = wid2 >> 2, wc2 = wid2 & 3, fr2 = lane2 & 15, fq2 = lane2 >> 4;
;   float* part = (float*)(smem + 139264);
;   float* rsb = part + 512;
;   float sq[2][2] = {{0.f, 0.f}, {0.f, 0.f}};
;   for (int bj = 0; bj < 2; ++bj) for (int m = 0; m < 4; ++m) {
;     for (int n = 0; n < 2; ++n) {
;       const int rl = wr2 * 64 + m * 16 + fq2 * 4, col = bc0 + bj * HALF + wc2 * 32 + n * 16 + fr2;
;       const f32x4 v0 = *(const f32x4*)(xin + (long)col * DM + n0 + rl) + acc[0][bj][m][n], v1 = *(const f32x4*)(xin + (long)col * DM + n0 + HALF + rl) + acc[1][bj][m][n];
;       if (mode != 2) { *(f32x4*)(xout + (long)col * DM + n0 + rl) = v0; *(f32x4*)(xout + (long)col * DM + n0 + HALF + rl) = v1; }
;       acc[0][bj][m][n] = v0; acc[1][bj][m][n] = v1;
;       sq[bj][n] += v0[0] * v0[0] + v0[1] * v0[1] + v0[2] * v0[2] + v0[3] * v0[3] + v1[0] * v1[0] + v1[1] * v1[1] + v1[2] * v1[2] + v1[3] * v1[3];
.LBB0_190:
	v_readlane_b32 s0, v255, 22
	v_readlane_b32 s1, v255, 23
	s_load_dwordx2 s[20:21], s[0:1], 0x90
	v_mbcnt_lo_u32_b32 v132, -1, 0
	v_mbcnt_hi_u32_b32 v132, -1, v132
	s_lshl_b64 s[18:19], s[16:17], 2
	v_add_u32_e32 v130, s3, v132
	v_and_b32_e32 v131, 63, v132
	v_readfirstlane_b32 s0, v130
	s_ashr_i32 s8, s0, 2
	s_bfe_u32 s1, s0, 0x20006
	v_and_b32_e32 v0, 15, v132
	s_andn2_b32 s8, s8, 63
	v_lshrrev_b32_e32 v132, 2, v132
	v_and_or_b32 v132, v132, 12, s8
	s_lshl_b32 s8, s1, 5
	s_or_b32 s8, s8, s14
	v_or_b32_e32 v134, s8, v0
	v_readlane_b32 s8, v255, 26
	v_readlane_b32 s9, v255, 27
	s_add_u32 s22, s8, s18
	v_ashrrev_i32_e32 v135, 31, v134
	s_addc_u32 s23, s9, s19
	v_ashrrev_i32_e32 v133, 31, v132
	v_lshlrev_b64 v[142:143], 12, v[134:135]
	v_lshl_add_u64 v[136:137], s[22:23], 0, v[142:143]
	v_lshlrev_b64 v[132:133], 2, v[132:133]
	v_lshl_add_u64 v[136:137], v[136:137], 0, v[132:133]
	v_mov_b32_e32 v230, v134
	v_ashrrev_i32_e32 v231, 31, v230
	v_lshlrev_b64 v[230:231], 12, v[230:231]
	v_lshl_add_u64 v[234:235], s[22:23], 0, v[230:231]
	v_lshl_add_u64 v[234:235], v[234:235], 0, v[132:133]
	v_or_b32_e32 v230, 16, v134
	v_ashrrev_i32_e32 v231, 31, v230
	v_lshlrev_b64 v[230:231], 12, v[230:231]
	v_lshl_add_u64 v[236:237], s[22:23], 0, v[230:231]
	v_lshl_add_u64 v[236:237], v[236:237], 0, v[132:133]
	v_or_b32_e32 v230, 0x80, v134
	v_ashrrev_i32_e32 v231, 31, v230
	v_lshlrev_b64 v[230:231], 12, v[230:231]
	v_lshl_add_u64 v[238:239], s[22:23], 0, v[230:231]
	v_lshl_add_u64 v[238:239], v[238:239], 0, v[132:133]
	v_or_b32_e32 v230, 0x90, v134
	v_ashrrev_i32_e32 v231, 31, v230
	v_lshlrev_b64 v[230:231], 12, v[230:231]
	v_lshl_add_u64 v[240:241], s[22:23], 0, v[230:231]
	v_lshl_add_u64 v[240:241], v[240:241], 0, v[132:133]
	global_load_dwordx4 v[152:155], v[234:235], off
	global_load_dwordx4 v[156:159], v[234:235], off offset:512
	global_load_dwordx4 v[160:163], v[236:237], off
	global_load_dwordx4 v[164:167], v[236:237], off offset:512
	global_load_dwordx4 v[168:171], v[234:235], off offset:64
	global_load_dwordx4 v[172:175], v[234:235], off offset:576
	global_load_dwordx4 v[176:179], v[236:237], off offset:64
	global_load_dwordx4 v[180:183], v[236:237], off offset:576
	global_load_dwordx4 v[184:187], v[234:235], off offset:128
	global_load_dwordx4 v[188:191], v[234:235], off offset:640
	global_load_dwordx4 v[192:195], v[236:237], off offset:128
	global_load_dwordx4 v[196:199], v[236:237], off offset:640
	global_load_dwordx4 v[200:203], v[234:235], off offset:192
	global_load_dwordx4 v[206:209], v[234:235], off offset:704
	global_load_dwordx4 v[210:213], v[236:237], off offset:192
	global_load_dwordx4 v[214:217], v[236:237], off offset:704
	global_load_dwordx4 v[218:221], v[238:239], off
	global_load_dwordx4 v[222:225], v[238:239], off offset:512
	global_load_dwordx4 v[226:229], v[240:241], off
	s_add_u32 s8, s52, s18
	s_addc_u32 s9, s53, s19
	s_waitcnt vmcnt(18)
	v_pk_add_f32 v[100:101], v[100:101], v[154:155]
	s_waitcnt vmcnt(18)
	v_pk_add_f32 v[98:99], v[98:99], v[152:153]
	global_load_dwordx4 v[152:155], v[240:241], off offset:512
	v_mul_f32_e32 v135, v99, v99
	v_fmac_f32_e32 v135, v98, v98
	v_fmac_f32_e32 v135, v100, v100
	v_fmac_f32_e32 v135, v101, v101
	s_waitcnt vmcnt(18)
	v_pk_add_f32 v[108:109], v[108:109], v[158:159]
	v_or_b32_e32 v140, 16, v134
	v_ashrrev_i32_e32 v141, 31, v140
	s_waitcnt vmcnt(18)
	v_pk_add_f32 v[106:107], v[106:107], v[156:157]
	global_load_dwordx4 v[156:159], v[238:239], off offset:576
	v_lshl_add_u64 v[138:139], s[8:9], 0, v[142:143]
	v_lshlrev_b64 v[140:141], 12, v[140:141]
	v_lshl_add_u64 v[138:139], v[138:139], 0, v[132:133]
	v_lshl_add_u64 v[142:143], s[22:23], 0, v[140:141]
	global_store_dwordx4 v[138:139], v[98:101], off
	global_store_dwordx4 v[138:139], v[106:109], off offset:512
	v_lshl_add_u64 v[142:143], v[142:143], 0, v[132:133]
	v_lshl_add_u64 v[140:141], s[8:9], 0, v[140:141]
	v_lshl_add_u64 v[140:141], v[140:141], 0, v[132:133]
	v_fmac_f32_e32 v135, v106, v106
	v_fmac_f32_e32 v135, v107, v107
	v_fmac_f32_e32 v135, v108, v108
	v_fmac_f32_e32 v135, v109, v109
	s_waitcnt vmcnt(20)
	v_pk_add_f32 v[124:125], v[124:125], v[162:163]
	s_waitcnt vmcnt(20)
	v_pk_add_f32 v[122:123], v[122:123], v[160:161]
	global_load_dwordx4 v[160:163], v[238:239], off offset:64
	s_waitcnt vmcnt(20)
	v_pk_add_f32 v[128:129], v[128:129], v[166:167]
	s_waitcnt vmcnt(20)
	v_pk_add_f32 v[126:127], v[126:127], v[164:165]
	global_load_dwordx4 v[164:167], v[240:241], off offset:64
	global_store_dwordx4 v[140:141], v[122:125], off
	global_store_dwordx4 v[140:141], v[126:129], off offset:512
	s_waitcnt vmcnt(22)
	v_pk_add_f32 v[112:113], v[112:113], v[170:171]
	s_waitcnt vmcnt(22)
	v_pk_add_f32 v[110:111], v[110:111], v[168:169]
	global_load_dwordx4 v[168:171], v[240:241], off offset:576
	s_waitcnt vmcnt(22)
	v_pk_add_f32 v[114:115], v[114:115], v[172:173]
	v_mul_f32_e32 v144, v111, v111
	v_fmac_f32_e32 v144, v110, v110
	v_fmac_f32_e32 v144, v112, v112
	v_fmac_f32_e32 v144, v113, v113
	v_fmac_f32_e32 v144, v114, v114
	s_waitcnt vmcnt(22)
	v_pk_add_f32 v[116:117], v[116:117], v[174:175]
	global_load_dwordx4 v[172:175], v[238:239], off offset:128
	v_fmac_f32_e32 v144, v115, v115
	v_fmac_f32_e32 v144, v116, v116
	global_store_dwordx4 v[138:139], v[110:113], off offset:64
	global_store_dwordx4 v[138:139], v[114:117], off offset:576
	v_fmac_f32_e32 v144, v117, v117
	v_add_f32_e32 v135, v135, v144
	s_waitcnt vmcnt(24)
	v_pk_add_f32 v[104:105], v[104:105], v[178:179]
	s_waitcnt vmcnt(24)
	v_pk_add_f32 v[102:103], v[102:103], v[176:177]
	global_load_dwordx4 v[176:179], v[238:239], off offset:640
	s_waitcnt vmcnt(24)
; DI float shflx(float v, int mask, int lane) { return __int_as_float(__builtin_amdgcn_ds_bpermute((lane ^ mask) << 2, __float_as_int(v))); }
; DI void resid_norm_epi(WVP char* smem, AccT& acc, int bc0, const float* xin, float* xout, int n0, int pc, int pr, unsigned epoch,
;                        u64* slab, const float* g, u16* xn, int mode) {
;     ...
;   for (int bj = 0; bj < 2; ++bj) for (int m = 0; m < 4; ++m) {
;     for (int n = 0; n < 2; ++n) {
;       const int rl = wr2 * 64 + m * 16 + fq2 * 4, col = bc0 + bj * HALF + wc2 * 32 + n * 16 + fr2;
;       const f32x4 v0 = *(const f32x4*)(xin + (long)col * DM + n0 + rl) + acc[0][bj][m][n], v1 = *(const f32x4*)(xin + (long)col * DM + n0 + HALF + rl) + acc[1][bj][m][n];
;       if (mode != 2) { *(f32x4*)(xout + (long)col * DM + n0 + rl) = v0; *(f32x4*)(xout + (long)col * DM + n0 + HALF + rl) = v1; }
;       acc[0][bj][m][n] = v0; acc[1][bj][m][n] = v1;
;       sq[bj][n] += v0[0] * v0[0] + v0[1] * v0[1] + v0[2] * v0[2] + v0[3] * v0[3] + v1[0] * v1[0] + v1[1] * v1[1] + v1[2] * v1[2] + v1[3] * v1[3];
;     }
;     if (m & 1) __builtin_amdgcn_sched_barrier(0);
;   }
;   for (int bj = 0; bj < 2; ++bj) for (int n = 0; n < 2; ++n) {
;     float sv = sq[bj][n]; sv += shflx(sv, 16, lane2); sv += shflx(sv, 32, lane2);
;     if (fq2 == 0) part[wr2 * 256 + bj * HALF + wc2 * 32 + n * 16 + fr2] = sv;
	v_pk_add_f32 v[120:121], v[120:121], v[182:183]
	s_waitcnt vmcnt(24)
	v_pk_add_f32 v[118:119], v[118:119], v[180:181]
	global_load_dwordx4 v[180:183], v[240:241], off offset:128
	global_store_dwordx4 v[140:141], v[102:105], off offset:64
	global_store_dwordx4 v[140:141], v[118:121], off offset:576
	s_waitcnt vmcnt(26)
	v_pk_add_f32 v[80:81], v[80:81], v[186:187]
	s_waitcnt vmcnt(26)
	v_pk_add_f32 v[78:79], v[78:79], v[184:185]
	global_load_dwordx4 v[184:187], v[240:241], off offset:640
	s_waitcnt vmcnt(26)
	v_pk_add_f32 v[82:83], v[82:83], v[188:189]
	v_mul_f32_e32 v144, v79, v79
	v_fmac_f32_e32 v144, v78, v78
	v_fmac_f32_e32 v144, v80, v80
	v_fmac_f32_e32 v144, v81, v81
	v_fmac_f32_e32 v144, v82, v82
	s_waitcnt vmcnt(26)
	v_pk_add_f32 v[84:85], v[84:85], v[190:191]
	global_load_dwordx4 v[188:191], v[238:239], off offset:704
	v_fmac_f32_e32 v144, v83, v83
	v_fmac_f32_e32 v144, v84, v84
	global_store_dwordx4 v[138:139], v[78:81], off offset:128
	global_store_dwordx4 v[138:139], v[82:85], off offset:640
	v_fmac_f32_e32 v144, v85, v85
	v_add_f32_e32 v135, v135, v144
	s_waitcnt vmcnt(28)
	v_pk_add_f32 v[92:93], v[92:93], v[194:195]
	s_waitcnt vmcnt(28)
	v_pk_add_f32 v[90:91], v[90:91], v[192:193]
	global_load_dwordx4 v[192:195], v[238:239], off offset:192
	s_waitcnt vmcnt(28)
	v_pk_add_f32 v[96:97], v[96:97], v[198:199]
	s_waitcnt vmcnt(28)
	v_pk_add_f32 v[94:95], v[94:95], v[196:197]
	global_load_dwordx4 v[196:199], v[240:241], off offset:192
	global_store_dwordx4 v[140:141], v[90:93], off offset:128
	global_store_dwordx4 v[140:141], v[94:97], off offset:640
	s_waitcnt vmcnt(30)
	v_pk_add_f32 v[68:69], v[68:69], v[202:203]
	s_waitcnt vmcnt(30)
	v_pk_add_f32 v[66:67], v[66:67], v[200:201]
	global_load_dwordx4 v[200:203], v[240:241], off offset:704
	v_mul_f32_e32 v136, v67, v67
	v_fmac_f32_e32 v136, v66, v66
	v_fmac_f32_e32 v136, v68, v68
	v_fmac_f32_e32 v136, v69, v69
	s_waitcnt vmcnt(30)
	v_pk_add_f32 v[74:75], v[74:75], v[206:207]
	s_nop 0
	v_fmac_f32_e32 v136, v74, v74
	s_waitcnt vmcnt(30)
	v_pk_add_f32 v[76:77], v[76:77], v[208:209]
	v_fmac_f32_e32 v136, v75, v75
	v_fmac_f32_e32 v136, v76, v76
	global_store_dwordx4 v[138:139], v[66:69], off offset:192
	global_store_dwordx4 v[138:139], v[74:77], off offset:704
	v_fmac_f32_e32 v136, v77, v77
	v_add_f32_e32 v144, v135, v136
	s_waitcnt vmcnt(31)
	v_pk_add_f32 v[72:73], v[72:73], v[212:213]
	s_waitcnt vmcnt(31)
	v_pk_add_f32 v[70:71], v[70:71], v[210:211]
	s_waitcnt vmcnt(30)
	v_pk_add_f32 v[88:89], v[88:89], v[216:217]
	s_waitcnt vmcnt(30)
	v_pk_add_f32 v[86:87], v[86:87], v[214:215]
	global_store_dwordx4 v[140:141], v[70:73], off offset:192
	global_store_dwordx4 v[140:141], v[86:89], off offset:704
	v_or_b32_e32 v136, 0x80, v134
	v_ashrrev_i32_e32 v137, 31, v136
	v_lshlrev_b64 v[136:137], 12, v[136:137]
	v_lshl_add_u64 v[138:139], s[22:23], 0, v[136:137]
	v_lshl_add_u64 v[138:139], v[138:139], 0, v[132:133]
	v_or_b32_e32 v134, 0x90, v134
	v_ashrrev_i32_e32 v135, 31, v134
	v_lshl_add_u64 v[136:137], s[8:9], 0, v[136:137]
	v_lshlrev_b64 v[146:147], 12, v[134:135]
	v_lshl_add_u64 v[136:137], v[136:137], 0, v[132:133]
	v_lshl_add_u64 v[134:135], s[22:23], 0, v[146:147]
	v_lshl_add_u64 v[134:135], v[134:135], 0, v[132:133]
	s_waitcnt vmcnt(31)
	v_pk_add_f32 v[52:53], v[52:53], v[220:221]
	s_waitcnt vmcnt(31)
	v_pk_add_f32 v[50:51], v[50:51], v[218:219]
	s_waitcnt vmcnt(30)
	v_pk_add_f32 v[56:57], v[56:57], v[224:225]
	s_waitcnt vmcnt(30)
	v_pk_add_f32 v[54:55], v[54:55], v[222:223]
	global_store_dwordx4 v[136:137], v[50:53], off
	global_store_dwordx4 v[136:137], v[54:57], off offset:512
	s_waitcnt vmcnt(31)
	v_pk_add_f32 v[60:61], v[60:61], v[228:229]
	s_waitcnt vmcnt(31)
	v_pk_add_f32 v[58:59], v[58:59], v[226:227]
	s_waitcnt vmcnt(30)
	v_pk_add_f32 v[62:63], v[62:63], v[152:153]
	v_lshl_add_u64 v[140:141], s[8:9], 0, v[146:147]
	v_lshl_add_u64 v[150:151], v[140:141], 0, v[132:133]
	s_waitcnt vmcnt(30)
	v_pk_add_f32 v[64:65], v[64:65], v[154:155]
	global_store_dwordx4 v[150:151], v[58:61], off
	global_store_dwordx4 v[150:151], v[62:65], off offset:512
	s_waitcnt vmcnt(31)
	v_pk_add_f32 v[48:49], v[48:49], v[158:159]
	s_waitcnt vmcnt(28)
	v_pk_add_f32 v[44:45], v[44:45], v[162:163]
	s_waitcnt vmcnt(28)
	v_pk_add_f32 v[42:43], v[42:43], v[160:161]
	s_waitcnt vmcnt(31)
	v_pk_add_f32 v[46:47], v[46:47], v[156:157]
	global_store_dwordx4 v[136:137], v[42:45], off offset:64
	global_store_dwordx4 v[136:137], v[46:49], off offset:576
	s_waitcnt vmcnt(29)
	v_pk_add_f32 v[36:37], v[36:37], v[166:167]
	s_waitcnt vmcnt(29)
	v_pk_add_f32 v[34:35], v[34:35], v[164:165]
	s_waitcnt vmcnt(26)
	v_pk_add_f32 v[40:41], v[40:41], v[170:171]
	s_waitcnt vmcnt(26)
	v_pk_add_f32 v[38:39], v[38:39], v[168:169]
	global_store_dwordx4 v[150:151], v[34:37], off offset:64
	global_store_dwordx4 v[150:151], v[38:41], off offset:576
	s_waitcnt vmcnt(27)
	v_pk_add_f32 v[20:21], v[20:21], v[174:175]
	s_waitcnt vmcnt(27)
	v_pk_add_f32 v[18:19], v[18:19], v[172:173]
	s_waitcnt vmcnt(24)
	v_pk_add_f32 v[28:29], v[28:29], v[178:179]
	s_waitcnt vmcnt(24)
	v_pk_add_f32 v[26:27], v[26:27], v[176:177]
	global_store_dwordx4 v[136:137], v[18:21], off offset:128
	global_store_dwordx4 v[136:137], v[26:29], off offset:640
	s_waitcnt vmcnt(25)
	v_pk_add_f32 v[24:25], v[24:25], v[182:183]
	s_waitcnt vmcnt(25)
	v_pk_add_f32 v[22:23], v[22:23], v[180:181]
	s_waitcnt vmcnt(22)
	v_pk_add_f32 v[32:33], v[32:33], v[186:187]
	s_waitcnt vmcnt(22)
	v_pk_add_f32 v[30:31], v[30:31], v[184:185]
	global_store_dwordx4 v[150:151], v[22:25], off offset:128
	global_store_dwordx4 v[150:151], v[30:33], off offset:640
	s_waitcnt vmcnt(23)
	v_pk_add_f32 v[16:17], v[16:17], v[190:191]
	s_waitcnt vmcnt(20)
	v_pk_add_f32 v[12:13], v[12:13], v[194:195]
	s_waitcnt vmcnt(20)
	v_pk_add_f32 v[10:11], v[10:11], v[192:193]
	s_waitcnt vmcnt(23)
	v_pk_add_f32 v[14:15], v[14:15], v[188:189]
	global_store_dwordx4 v[136:137], v[10:13], off offset:192
	global_store_dwordx4 v[136:137], v[14:17], off offset:704
	s_waitcnt vmcnt(21)
	v_pk_add_f32 v[4:5], v[4:5], v[198:199]
	s_waitcnt vmcnt(21)
	v_pk_add_f32 v[2:3], v[2:3], v[196:197]
	s_waitcnt vmcnt(18)
	v_pk_add_f32 v[8:9], v[8:9], v[202:203]
	s_waitcnt vmcnt(18)
	v_pk_add_f32 v[6:7], v[6:7], v[200:201]
	global_store_dwordx4 v[150:151], v[2:5], off offset:192
	global_store_dwordx4 v[150:151], v[6:9], off offset:704
	v_lshlrev_b32_e32 v132, 2, v131
	v_xor_b32_e32 v133, 64, v132
	ds_bpermute_b32 v134, v133, v144
	v_xor_b32_e32 v132, 0x80, v132
	v_cmp_gt_u32_e32 vcc, 16, v131
	s_and_b32 s0, s0, 0x3fffff00
	s_lshl_b32 s0, s0, 2
	s_waitcnt lgkmcnt(0)
	v_add_f32_e32 v131, v144, v134
	ds_bpermute_b32 v134, v132, v131
	s_add_i32 s0, s0, 0
	s_lshl_b32 s1, s1, 7
	s_add_i32 s0, s0, s1
	s_add_i32 s0, s0, 0x22000
	v_lshl_add_u32 v0, v0, 2, s0
	s_and_saveexec_b64 s[8:9], vcc
	s_cbranch_execz .LBB0_192
	s_waitcnt lgkmcnt(0)
	v_add_f32_e32 v131, v131, v134
	ds_write_b32 v0, v131
